# MoBA prologue: qb<=3 units skip kbar load + 2 barriers + selection table; gate q-row loads issued before kbar wait
# speedup vs baseline: 1.0057x; 1.0030x over previous
; template<int THRL,int MODE,int DM,bool DRY=false> __device__ __forceinline__ void attn_unit(int b,int h,int qb,const bf16*Q,const bf16*__restrict__ K,const bf16*__restrict__ V,bf16*O,const bf16*__restrict__ Z,const float*__restrict__ XP,const int*__restrict__ TS,volatile unsigned*lw,unsigned nxt,cha ...
;     ...
;   const bf16*Qw=Q+(rowbase+q0+wid*QBLK)*DM+h*D;
;   bf16x8 qr[4];
;   #pragma unroll
;   for(int d0=0;d0<4;++d0)qr[d0]=*reinterpret_cast<const bf16x8*>(&Qw[(long)r32*DM+d0*16+hi*8]);
;   const bf16*Kh=K+rowbase*DM+h*D,*Vh=V+rowbase*DM+h*D;
;   const unsigned lds0=(unsigned)(uintptr_t)shm;
;   float*wsf=(float*)(shm+LDS_WS)+wid*64;
;   const bf16*ksrc_=Kh+(long)lane*DM+wid*8; int tskip=0,fixedref=0; const bf16*ksrc=ksrc_;
;   const bf16*vsrc_=Vh+(long)(16*(wid&3)+(lane>>2))*DM+(wid>>2)*32+(lane&3)*8; const bf16*vsrc=vsrc_;
;   const unsigned kdst=lds0+LDS_K+wid*1024, vdst=lds0+LDS_V+wid*1024;
;     ...
;   const int vb0=(int)(lds0+LDS_V)+((lane>>4)&1)*32+(lane&3)*8+(4*hi+((lane&15)>>2))*64;
;   const char*Kbase=shm+LDS_K; bf16x8 kf[8];
;   const lds_cptr shm3=(lds_cptr)shm; const lds_cptr kp0=shm3+LDS_K+hi*1024+r32*16; const lds_cptr vp0=shm3+LDS_V+((lane>>4)&1)*32+(lane&3)*8+(4*hi+((lane&15)>>2))*64;
;   int NT=(q0+QB)/KVBLK;
;   const int qrel=wid*QBLK+r32;
;   unsigned sel=0u;
;   if constexpr(MODE==1){
;     { const int tsv=__builtin_amdgcn_readfirstlane(TS[qb]); tskip=tsv&0xffff; fixedref=(tsv>>16)&1; }
;     ksrc=ksrc_+(long)tskip*KVBLK*DM; vsrc=vsrc_+(long)tskip*KVBLK*DM; NT-=tskip;
;   }
;   const lds_cptr fsl=(lds_cptr)shm+XOFF+16*hi+tskip*256;
;     ...
;   DMA_K(0,0);DMA_V(0,0);DMA_K(1,SLOTB);
;   float mhat=0.f,l_reg=0.f;f32x16 o[2];o[0]=f32x16{};o[1]=f32x16{};f32x16 negm=f32x16{}; if constexpr(MODE==0){asm volatile("":"+v"(negm));}
;     ...
;   const f32x16 czero_=f32x16{};
;     ...
;   bool resc=false;
;     ...
;   f32x16 pA0,pA1,pB0,pB1;
;   int sl_prev=0,sl_cur=0,sl_next=SLOTB;
;     ...
;   DMA_K(2,2*SLOTB);
;   if constexpr(MODE==1){ float*fs=(float*)(shm+XOFF); for(int i=tid+64*tskip;i<q0+QB;i+=NW*64)fs[i]=XP[i]; }
;   if constexpr(MODE==0){
;     float*kbs=(float*)(shm+XOFF); unsigned*sm=(unsigned*)(shm+XOFF+2048);
;     kbs[tid]=XP[tid];
;     asm volatile("s_waitcnt vmcnt(0) lgkmcnt(0)\n\ts_barrier":::"memory");
;     if(tid<QB){ unsigned m=(1u<<qb)-1u;
;       if(qb>3){ const bf16*qp=Q+(rowbase+q0+tid)*DM+h*D; float g[8];
;         _Pragma("unroll") for(int n=0;n<8;++n)g[n]=0.f;
.LBB0_894:
	s_or_b64 exec, exec, s[8:9]
	s_ashr_i32 s8, s10, 31
	s_lshr_b32 s8, s8, 25
	s_add_i32 s8, s10, s8
	s_ashr_i32 s9, s8, 7
	s_and_b32 s8, s8, 0xffffff80
	s_sub_i32 s64, s10, s8
	s_ashr_i32 s65, s64, 31
	s_sub_i32 s92, 0, s9
	s_sub_i32 s95, 7, s9
	s_ashr_i32 s70, s64, 4
	s_lshl_b64 s[8:9], s[64:65], 11
	s_add_u32 s10, s26, s8
	v_mov_b32_e32 v224, v220
	s_addc_u32 s11, s45, s9
	s_ashr_i32 s71, s70, 31
	v_readfirstlane_b32 s93, v224
	s_ashr_i32 s65, s93, 6
	s_lshl_b64 s[8:9], s[70:71], 11
	s_lshl_b32 s94, s95, 8
	s_add_u32 s8, s8, s94
	s_addc_u32 s9, s9, 0
	s_lshl_b32 s96, s65, 5
	s_ashr_i32 s12, s96, 31
	s_add_u32 s14, s8, s96
	s_addc_u32 s12, s9, s12
	s_mulk_i32 s12, 0x1a00
	s_mul_hi_u32 s13, s14, 0x1a00
	s_add_i32 s13, s13, s12
	s_mul_i32 s12, s14, 0x1a00
	s_lshl_b64 s[60:61], s[12:13], 1
	s_add_u32 s12, s28, s60
	s_addc_u32 s13, s29, s61
	s_lshl_b32 s14, s64, 6
	s_and_b32 s14, s14, 0x3c0
	s_lshl_b32 s62, s14, 1
	s_add_u32 s58, s12, s62
	s_addc_u32 s59, s13, 0
	s_mul_i32 s15, s70, 0x1a00000
	s_mul_hi_i32 s14, s70, 0x1a00000
	s_add_u32 s12, s47, s15
	v_and_b32_e32 v237, 31, v224
	s_addc_u32 s13, s84, s14
	v_mul_u32_u24_e32 v16, 0x1a00, v237
	s_add_u32 s12, s12, s62
	v_bfe_u32 v238, v224, 5, 1
	v_lshlrev_b32_e32 v16, 1, v16
	s_addc_u32 s13, s13, 0
	v_lshl_or_b32 v222, v238, 4, v16
	s_add_u32 s15, s85, s15
	v_and_b32_e32 v239, 63, v224
	v_lshl_add_u64 v[16:17], s[58:59], 0, v[222:223]
	s_addc_u32 s16, s86, s14
	flat_load_dwordx4 v[156:159], v[16:17]
	flat_load_dwordx4 v[152:155], v[16:17] offset:32
	flat_load_dwordx4 v[148:151], v[16:17] offset:64
	flat_load_dwordx4 v[144:147], v[16:17] offset:96
	s_add_u32 s14, s15, s62
	v_mul_u32_u24_e32 v16, 0x1a00, v239
	s_addc_u32 s15, s16, 0
	v_lshlrev_b32_e32 v222, 1, v16
	s_lshl_b32 s66, s65, 3
	v_lshl_add_u64 v[16:17], s[12:13], 0, v[222:223]
	s_ashr_i32 s67, s66, 31
	v_lshl_add_u64 v[80:81], s[66:67], 1, v[16:17]
	s_lshl_b32 s12, s65, 4
	v_bfe_u32 v16, v224, 2, 4
	v_and_or_b32 v16, s12, 48, v16
	s_ashr_i32 s12, s93, 3
	s_and_b32 s68, s12, 0xffffffe0
	v_mul_u32_u24_e32 v16, 0x1a00, v16
	s_ashr_i32 s69, s68, 31
	s_lshl_b32 s24, s65, 10
	v_lshlrev_b32_e32 v212, 1, v16
	v_mov_b32_e32 v213, v223
	v_lshlrev_b32_e32 v242, 3, v224
	s_cmp_lg_u32 0, -1
	v_lshl_add_u64 v[16:17], s[14:15], 0, v[212:213]
	v_and_b32_e32 v241, 24, v242
	s_cselect_b32 s12, 0, 0
	v_lshl_add_u64 v[16:17], s[68:69], 1, v[16:17]
	v_lshlrev_b32_e32 v18, 1, v241
	v_mov_b32_e32 v19, v223
	s_add_i32 s91, s24, s12
	s_mov_b32 s12, m0
	s_mov_b32 m0, s91
	s_nop 0
	global_load_lds_dwordx4 v[80:81], off
	s_mov_b32 m0, s12
	v_lshl_add_u64 v[82:83], v[16:17], 0, v[18:19]
	s_add_i32 s71, s91, 0x6000
	s_mov_b32 s12, m0
	s_mov_b32 m0, s71
	s_nop 0
	global_load_lds_dwordx4 v[82:83], off
	s_mov_b32 m0, s12
	v_lshl_add_u64 v[16:17], v[80:81], 0, s[34:35]
	s_add_i32 s12, s91, 0x2000
	s_mov_b32 s13, m0
	s_mov_b32 m0, s12
	s_nop 0
	global_load_lds_dwordx4 v[16:17], off
	s_mov_b32 m0, s13
	v_mov_b64_e32 v[30:31], v[14:15]
	v_mov_b64_e32 v[28:29], v[12:13]
	v_mov_b64_e32 v[26:27], v[10:11]
	v_mov_b64_e32 v[24:25], v[8:9]
	v_mov_b64_e32 v[22:23], v[6:7]
	v_mov_b64_e32 v[20:21], v[4:5]
	v_mov_b64_e32 v[18:19], v[2:3]
	v_mov_b64_e32 v[16:17], v[0:1]
	v_lshl_add_u64 v[32:33], v[80:81], 0, s[36:37]
	v_ashrrev_i32_e32 v225, 31, v224
	s_add_i32 s12, s91, 0x4000
	s_mov_b32 s13, m0
	s_mov_b32 m0, s12
	s_nop 0
	global_load_lds_dwordx4 v[32:33], off
	s_mov_b32 m0, s13
	s_cmp_lt_u32 s95, 4
	s_cbranch_scc1 .LBB0_898
	s_cmp_gt_u32 s65, 3
	s_cbranch_scc1 .Lmoba_no_qrow
	v_lshl_add_u64 v[34:35], s[8:9], 0, v[224:225]
	v_mov_b64_e32 v[36:37], s[28:29]
	s_movk_i32 s98, 0x3400
	v_mad_u64_u32 v[36:37], s[100:101], v34, s98, v[36:37]
	v_mad_i32_i24 v37, v35, s98, v37
	s_mov_b32 s63, s25
	v_lshl_add_u64 v[34:35], v[36:37], 0, s[62:63]
	flat_load_dwordx4 v[84:87], v[34:35]
	flat_load_dwordx4 v[88:91], v[34:35] offset:16
	flat_load_dwordx4 v[92:95], v[34:35] offset:32
	flat_load_dwordx4 v[96:99], v[34:35] offset:48
	flat_load_dwordx4 v[100:103], v[34:35] offset:64
	flat_load_dwordx4 v[104:107], v[34:35] offset:80
	flat_load_dwordx4 v[108:111], v[34:35] offset:96
	flat_load_dwordx4 v[112:115], v[34:35] offset:112
.Lmoba_no_qrow:
	v_lshl_add_u64 v[32:33], v[224:225], 2, s[10:11]
	flat_load_dword v32, v[32:33]
	v_lshl_add_u32 v33, v224, 2, 0
	v_add_u32_e32 v33, 0x15000, v33
	s_movk_i32 s10, 0x100
	v_cmp_gt_i32_e32 vcc, s10, v224
	s_waitcnt vmcnt(0) lgkmcnt(0)
	ds_write_b32 v33, v32
	s_waitcnt vmcnt(0) lgkmcnt(0)
	s_barrier
	s_and_saveexec_b64 s[72:73], vcc
	s_cbranch_execz .LBB0_898
	s_lshl_b32 s10, -1, s95
	s_not_b32 s10, s10
	s_cmp_lt_u32 s95, 4
	v_mov_b32_e32 v32, s10
	s_cbranch_scc1 .LBB0_897
; template<int THRL,int MODE,int DM,bool DRY=false> __device__ __forceinline__ void attn_unit(int b,int h,int qb,const bf16*Q,const bf16*__restrict__ K,const bf16*__restrict__ V,bf16*O,const bf16*__restrict__ Z,const float*__restrict__ XP,const int*__restrict__ TS,volatile unsigned*lw,unsigned nxt,cha ...
;     ...
;       if(qb>3){ const bf16*qp=Q+(rowbase+q0+tid)*DM+h*D; float g[8];
;         _Pragma("unroll") for(int n=0;n<8;++n)g[n]=0.f;
;         _Pragma("unroll") for(int c=0;c<8;++c){ const bf16x8 qv=*reinterpret_cast<const bf16x8*>(qp+c*8);
;           _Pragma("unroll") for(int j=0;j<8;++j){ const float qf=__uint_as_float(((unsigned)(unsigned short)qv[j])<<16);
;             _Pragma("unroll") for(int n=0;n<8;++n)g[n]+=qf*kbs[n*64+c*8+j]; } }
	s_mov_b32 s10, 0xff800000
	s_cmp_lg_u32 s95, 4
	s_cselect_b64 s[74:75], -1, 0
	v_mov_b32_e32 v74, 0x15000
	v_mov_b32_e32 v32, 0
	v_mov_b32_e32 v33, 0
	v_mov_b32_e32 v34, 0
	v_mov_b32_e32 v35, 0
	v_mov_b32_e32 v36, 0
	v_mov_b32_e32 v37, 0
	v_mov_b32_e32 v38, 0
	v_mov_b32_e32 v39, 0
	ds_read_b128 v[42:45], v74 offset:0
	ds_read_b128 v[46:49], v74 offset:256
	ds_read_b128 v[50:53], v74 offset:512
	ds_read_b128 v[54:57], v74 offset:768
	ds_read_b128 v[58:61], v74 offset:1024
	ds_read_b128 v[62:65], v74 offset:1280
	ds_read_b128 v[66:69], v74 offset:1536
	ds_read_b128 v[70:73], v74 offset:1792
	s_waitcnt vmcnt(0) lgkmcnt(0)
	ds_read_b128 v[116:119], v74 offset:16
	ds_read_b128 v[120:123], v74 offset:272
	ds_read_b128 v[124:127], v74 offset:528
	ds_read_b128 v[128:131], v74 offset:784
	ds_read_b128 v[132:135], v74 offset:1040
	ds_read_b128 v[136:139], v74 offset:1296
	ds_read_b128 v[140:143], v74 offset:1552
	ds_read_b128 v[76:79], v74 offset:1808
	s_waitcnt lgkmcnt(8)
	v_lshlrev_b32_e32 v40, 16, v84
	v_fmac_f32_e32 v39, v42, v40
	v_fmac_f32_e32 v38, v46, v40
	v_fmac_f32_e32 v37, v50, v40
	v_fmac_f32_e32 v36, v54, v40
	v_fmac_f32_e32 v35, v58, v40
	v_fmac_f32_e32 v34, v62, v40
	v_fmac_f32_e32 v33, v66, v40
	v_fmac_f32_e32 v32, v70, v40
	v_and_b32_e32 v41, 0xffff0000, v84
	v_fmac_f32_e32 v39, v43, v41
	v_fmac_f32_e32 v38, v47, v41
	v_fmac_f32_e32 v37, v51, v41
	v_fmac_f32_e32 v36, v55, v41
	v_fmac_f32_e32 v35, v59, v41
	v_fmac_f32_e32 v34, v63, v41
	v_fmac_f32_e32 v33, v67, v41
	v_fmac_f32_e32 v32, v71, v41
	v_lshlrev_b32_e32 v40, 16, v85
	v_fmac_f32_e32 v39, v44, v40
	v_fmac_f32_e32 v38, v48, v40
	v_fmac_f32_e32 v37, v52, v40
	v_fmac_f32_e32 v36, v56, v40
	v_fmac_f32_e32 v35, v60, v40
	v_fmac_f32_e32 v34, v64, v40
	v_fmac_f32_e32 v33, v68, v40
	v_fmac_f32_e32 v32, v72, v40
	v_and_b32_e32 v41, 0xffff0000, v85
	v_fmac_f32_e32 v39, v45, v41
	v_fmac_f32_e32 v38, v49, v41
	v_fmac_f32_e32 v37, v53, v41
	v_fmac_f32_e32 v36, v57, v41
	v_fmac_f32_e32 v35, v61, v41
	v_fmac_f32_e32 v34, v65, v41
	v_fmac_f32_e32 v33, v69, v41
	v_fmac_f32_e32 v32, v73, v41
	ds_read_b128 v[42:45], v74 offset:32
	ds_read_b128 v[46:49], v74 offset:288
	ds_read_b128 v[50:53], v74 offset:544
	ds_read_b128 v[54:57], v74 offset:800
	ds_read_b128 v[58:61], v74 offset:1056
	ds_read_b128 v[62:65], v74 offset:1312
	ds_read_b128 v[66:69], v74 offset:1568
	ds_read_b128 v[70:73], v74 offset:1824
	s_waitcnt lgkmcnt(8)
	v_lshlrev_b32_e32 v40, 16, v86
	v_fmac_f32_e32 v39, v116, v40
	v_fmac_f32_e32 v38, v120, v40
	v_fmac_f32_e32 v37, v124, v40
	v_fmac_f32_e32 v36, v128, v40
	v_fmac_f32_e32 v35, v132, v40
	v_fmac_f32_e32 v34, v136, v40
	v_fmac_f32_e32 v33, v140, v40
	v_fmac_f32_e32 v32, v76, v40
	v_and_b32_e32 v41, 0xffff0000, v86
	v_fmac_f32_e32 v39, v117, v41
	v_fmac_f32_e32 v38, v121, v41
	v_fmac_f32_e32 v37, v125, v41
	v_fmac_f32_e32 v36, v129, v41
	v_fmac_f32_e32 v35, v133, v41
	v_fmac_f32_e32 v34, v137, v41
	v_fmac_f32_e32 v33, v141, v41
	v_fmac_f32_e32 v32, v77, v41
	v_lshlrev_b32_e32 v40, 16, v87
	v_fmac_f32_e32 v39, v118, v40
	v_fmac_f32_e32 v38, v122, v40
	v_fmac_f32_e32 v37, v126, v40
	v_fmac_f32_e32 v36, v130, v40
	v_fmac_f32_e32 v35, v134, v40
	v_fmac_f32_e32 v34, v138, v40
	v_fmac_f32_e32 v33, v142, v40
	v_fmac_f32_e32 v32, v78, v40
	v_and_b32_e32 v41, 0xffff0000, v87
	v_fmac_f32_e32 v39, v119, v41
	v_fmac_f32_e32 v38, v123, v41
	v_fmac_f32_e32 v37, v127, v41
	v_fmac_f32_e32 v36, v131, v41
	v_fmac_f32_e32 v35, v135, v41
	v_fmac_f32_e32 v34, v139, v41
	v_fmac_f32_e32 v33, v143, v41
	v_fmac_f32_e32 v32, v79, v41
	ds_read_b128 v[116:119], v74 offset:48
	ds_read_b128 v[120:123], v74 offset:304
	ds_read_b128 v[124:127], v74 offset:560
	ds_read_b128 v[128:131], v74 offset:816
	ds_read_b128 v[132:135], v74 offset:1072
	ds_read_b128 v[136:139], v74 offset:1328
	ds_read_b128 v[140:143], v74 offset:1584
	ds_read_b128 v[76:79], v74 offset:1840
	s_waitcnt lgkmcnt(8)
	v_lshlrev_b32_e32 v40, 16, v88
	v_fmac_f32_e32 v39, v42, v40
	v_fmac_f32_e32 v38, v46, v40
	v_fmac_f32_e32 v37, v50, v40
	v_fmac_f32_e32 v36, v54, v40
	v_fmac_f32_e32 v35, v58, v40
	v_fmac_f32_e32 v34, v62, v40
	v_fmac_f32_e32 v33, v66, v40
	v_fmac_f32_e32 v32, v70, v40
	v_and_b32_e32 v41, 0xffff0000, v88
	v_fmac_f32_e32 v39, v43, v41
	v_fmac_f32_e32 v38, v47, v41
	v_fmac_f32_e32 v37, v51, v41
	v_fmac_f32_e32 v36, v55, v41
	v_fmac_f32_e32 v35, v59, v41
	v_fmac_f32_e32 v34, v63, v41
	v_fmac_f32_e32 v33, v67, v41
	v_fmac_f32_e32 v32, v71, v41
	v_lshlrev_b32_e32 v40, 16, v89
	v_fmac_f32_e32 v39, v44, v40
	v_fmac_f32_e32 v38, v48, v40
	v_fmac_f32_e32 v37, v52, v40
	v_fmac_f32_e32 v36, v56, v40
	v_fmac_f32_e32 v35, v60, v40
	v_fmac_f32_e32 v34, v64, v40
	v_fmac_f32_e32 v33, v68, v40
	v_fmac_f32_e32 v32, v72, v40
	v_and_b32_e32 v41, 0xffff0000, v89
	v_fmac_f32_e32 v39, v45, v41
	v_fmac_f32_e32 v38, v49, v41
	v_fmac_f32_e32 v37, v53, v41
	v_fmac_f32_e32 v36, v57, v41
	v_fmac_f32_e32 v35, v61, v41
	v_fmac_f32_e32 v34, v65, v41
	v_fmac_f32_e32 v33, v69, v41
	v_fmac_f32_e32 v32, v73, v41
	ds_read_b128 v[42:45], v74 offset:64
	ds_read_b128 v[46:49], v74 offset:320
	ds_read_b128 v[50:53], v74 offset:576
	ds_read_b128 v[54:57], v74 offset:832
	ds_read_b128 v[58:61], v74 offset:1088
	ds_read_b128 v[62:65], v74 offset:1344
	ds_read_b128 v[66:69], v74 offset:1600
	ds_read_b128 v[70:73], v74 offset:1856
	s_waitcnt lgkmcnt(8)
; template<int THRL,int MODE,int DM,bool DRY=false> __device__ __forceinline__ void attn_unit(int b,int h,int qb,const bf16*Q,const bf16*__restrict__ K,const bf16*__restrict__ V,bf16*O,const bf16*__restrict__ Z,const float*__restrict__ XP,const int*__restrict__ TS,volatile unsigned*lw,unsigned nxt,cha ...
;     ...
;         _Pragma("unroll") for(int c=0;c<8;++c){ const bf16x8 qv=*reinterpret_cast<const bf16x8*>(qp+c*8);
;           _Pragma("unroll") for(int j=0;j<8;++j){ const float qf=__uint_as_float(((unsigned)(unsigned short)qv[j])<<16);
;             _Pragma("unroll") for(int n=0;n<8;++n)g[n]+=qf*kbs[n*64+c*8+j]; } }
	v_lshlrev_b32_e32 v40, 16, v90
	v_fmac_f32_e32 v39, v116, v40
	v_fmac_f32_e32 v38, v120, v40
	v_fmac_f32_e32 v37, v124, v40
	v_fmac_f32_e32 v36, v128, v40
	v_fmac_f32_e32 v35, v132, v40
	v_fmac_f32_e32 v34, v136, v40
	v_fmac_f32_e32 v33, v140, v40
	v_fmac_f32_e32 v32, v76, v40
	v_and_b32_e32 v41, 0xffff0000, v90
	v_fmac_f32_e32 v39, v117, v41
	v_fmac_f32_e32 v38, v121, v41
	v_fmac_f32_e32 v37, v125, v41
	v_fmac_f32_e32 v36, v129, v41
	v_fmac_f32_e32 v35, v133, v41
	v_fmac_f32_e32 v34, v137, v41
	v_fmac_f32_e32 v33, v141, v41
	v_fmac_f32_e32 v32, v77, v41
	v_lshlrev_b32_e32 v40, 16, v91
	v_fmac_f32_e32 v39, v118, v40
	v_fmac_f32_e32 v38, v122, v40
	v_fmac_f32_e32 v37, v126, v40
	v_fmac_f32_e32 v36, v130, v40
	v_fmac_f32_e32 v35, v134, v40
	v_fmac_f32_e32 v34, v138, v40
	v_fmac_f32_e32 v33, v142, v40
	v_fmac_f32_e32 v32, v78, v40
	v_and_b32_e32 v41, 0xffff0000, v91
	v_fmac_f32_e32 v39, v119, v41
	v_fmac_f32_e32 v38, v123, v41
	v_fmac_f32_e32 v37, v127, v41
	v_fmac_f32_e32 v36, v131, v41
	v_fmac_f32_e32 v35, v135, v41
	v_fmac_f32_e32 v34, v139, v41
	v_fmac_f32_e32 v33, v143, v41
	v_fmac_f32_e32 v32, v79, v41
	ds_read_b128 v[116:119], v74 offset:80
	ds_read_b128 v[120:123], v74 offset:336
	ds_read_b128 v[124:127], v74 offset:592
	ds_read_b128 v[128:131], v74 offset:848
	ds_read_b128 v[132:135], v74 offset:1104
	ds_read_b128 v[136:139], v74 offset:1360
	ds_read_b128 v[140:143], v74 offset:1616
	ds_read_b128 v[76:79], v74 offset:1872
	s_waitcnt lgkmcnt(8)
	v_lshlrev_b32_e32 v40, 16, v92
	v_fmac_f32_e32 v39, v42, v40
	v_fmac_f32_e32 v38, v46, v40
	v_fmac_f32_e32 v37, v50, v40
	v_fmac_f32_e32 v36, v54, v40
	v_fmac_f32_e32 v35, v58, v40
	v_fmac_f32_e32 v34, v62, v40
	v_fmac_f32_e32 v33, v66, v40
	v_fmac_f32_e32 v32, v70, v40
	v_and_b32_e32 v41, 0xffff0000, v92
	v_fmac_f32_e32 v39, v43, v41
	v_fmac_f32_e32 v38, v47, v41
	v_fmac_f32_e32 v37, v51, v41
	v_fmac_f32_e32 v36, v55, v41
	v_fmac_f32_e32 v35, v59, v41
	v_fmac_f32_e32 v34, v63, v41
	v_fmac_f32_e32 v33, v67, v41
	v_fmac_f32_e32 v32, v71, v41
	v_lshlrev_b32_e32 v40, 16, v93
	v_fmac_f32_e32 v39, v44, v40
	v_fmac_f32_e32 v38, v48, v40
	v_fmac_f32_e32 v37, v52, v40
	v_fmac_f32_e32 v36, v56, v40
	v_fmac_f32_e32 v35, v60, v40
	v_fmac_f32_e32 v34, v64, v40
	v_fmac_f32_e32 v33, v68, v40
	v_fmac_f32_e32 v32, v72, v40
	v_and_b32_e32 v41, 0xffff0000, v93
	v_fmac_f32_e32 v39, v45, v41
	v_fmac_f32_e32 v38, v49, v41
	v_fmac_f32_e32 v37, v53, v41
	v_fmac_f32_e32 v36, v57, v41
	v_fmac_f32_e32 v35, v61, v41
	v_fmac_f32_e32 v34, v65, v41
	v_fmac_f32_e32 v33, v69, v41
	v_fmac_f32_e32 v32, v73, v41
	ds_read_b128 v[42:45], v74 offset:96
	ds_read_b128 v[46:49], v74 offset:352
	ds_read_b128 v[50:53], v74 offset:608
	ds_read_b128 v[54:57], v74 offset:864
	ds_read_b128 v[58:61], v74 offset:1120
	ds_read_b128 v[62:65], v74 offset:1376
	ds_read_b128 v[66:69], v74 offset:1632
	ds_read_b128 v[70:73], v74 offset:1888
	s_waitcnt lgkmcnt(8)
	v_lshlrev_b32_e32 v40, 16, v94
	v_fmac_f32_e32 v39, v116, v40
	v_fmac_f32_e32 v38, v120, v40
	v_fmac_f32_e32 v37, v124, v40
	v_fmac_f32_e32 v36, v128, v40
	v_fmac_f32_e32 v35, v132, v40
	v_fmac_f32_e32 v34, v136, v40
	v_fmac_f32_e32 v33, v140, v40
	v_fmac_f32_e32 v32, v76, v40
	v_and_b32_e32 v41, 0xffff0000, v94
	v_fmac_f32_e32 v39, v117, v41
	v_fmac_f32_e32 v38, v121, v41
	v_fmac_f32_e32 v37, v125, v41
	v_fmac_f32_e32 v36, v129, v41
	v_fmac_f32_e32 v35, v133, v41
	v_fmac_f32_e32 v34, v137, v41
	v_fmac_f32_e32 v33, v141, v41
	v_fmac_f32_e32 v32, v77, v41
	v_lshlrev_b32_e32 v40, 16, v95
	v_fmac_f32_e32 v39, v118, v40
	v_fmac_f32_e32 v38, v122, v40
	v_fmac_f32_e32 v37, v126, v40
	v_fmac_f32_e32 v36, v130, v40
	v_fmac_f32_e32 v35, v134, v40
	v_fmac_f32_e32 v34, v138, v40
	v_fmac_f32_e32 v33, v142, v40
	v_fmac_f32_e32 v32, v78, v40
	v_and_b32_e32 v41, 0xffff0000, v95
	v_fmac_f32_e32 v39, v119, v41
	v_fmac_f32_e32 v38, v123, v41
	v_fmac_f32_e32 v37, v127, v41
	v_fmac_f32_e32 v36, v131, v41
	v_fmac_f32_e32 v35, v135, v41
	v_fmac_f32_e32 v34, v139, v41
	v_fmac_f32_e32 v33, v143, v41
	v_fmac_f32_e32 v32, v79, v41
	ds_read_b128 v[116:119], v74 offset:112
	ds_read_b128 v[120:123], v74 offset:368
	ds_read_b128 v[124:127], v74 offset:624
	ds_read_b128 v[128:131], v74 offset:880
	ds_read_b128 v[132:135], v74 offset:1136
	ds_read_b128 v[136:139], v74 offset:1392
	ds_read_b128 v[140:143], v74 offset:1648
	ds_read_b128 v[76:79], v74 offset:1904
	s_waitcnt lgkmcnt(8)
	v_lshlrev_b32_e32 v40, 16, v96
	v_fmac_f32_e32 v39, v42, v40
	v_fmac_f32_e32 v38, v46, v40
	v_fmac_f32_e32 v37, v50, v40
	v_fmac_f32_e32 v36, v54, v40
	v_fmac_f32_e32 v35, v58, v40
	v_fmac_f32_e32 v34, v62, v40
	v_fmac_f32_e32 v33, v66, v40
	v_fmac_f32_e32 v32, v70, v40
	v_and_b32_e32 v41, 0xffff0000, v96
	v_fmac_f32_e32 v39, v43, v41
	v_fmac_f32_e32 v38, v47, v41
	v_fmac_f32_e32 v37, v51, v41
	v_fmac_f32_e32 v36, v55, v41
	v_fmac_f32_e32 v35, v59, v41
	v_fmac_f32_e32 v34, v63, v41
	v_fmac_f32_e32 v33, v67, v41
	v_fmac_f32_e32 v32, v71, v41
	v_lshlrev_b32_e32 v40, 16, v97
	v_fmac_f32_e32 v39, v44, v40
	v_fmac_f32_e32 v38, v48, v40
	v_fmac_f32_e32 v37, v52, v40
	v_fmac_f32_e32 v36, v56, v40
	v_fmac_f32_e32 v35, v60, v40
	v_fmac_f32_e32 v34, v64, v40
	v_fmac_f32_e32 v33, v68, v40
	v_fmac_f32_e32 v32, v72, v40
	v_and_b32_e32 v41, 0xffff0000, v97
	v_fmac_f32_e32 v39, v45, v41
	v_fmac_f32_e32 v38, v49, v41
	v_fmac_f32_e32 v37, v53, v41
	v_fmac_f32_e32 v36, v57, v41
	v_fmac_f32_e32 v35, v61, v41
	v_fmac_f32_e32 v34, v65, v41
	v_fmac_f32_e32 v33, v69, v41
	v_fmac_f32_e32 v32, v73, v41
	ds_read_b128 v[42:45], v74 offset:128
	ds_read_b128 v[46:49], v74 offset:384
	ds_read_b128 v[50:53], v74 offset:640
	ds_read_b128 v[54:57], v74 offset:896
	ds_read_b128 v[58:61], v74 offset:1152
	ds_read_b128 v[62:65], v74 offset:1408
	ds_read_b128 v[66:69], v74 offset:1664
	ds_read_b128 v[70:73], v74 offset:1920
	s_waitcnt lgkmcnt(8)
; template<int THRL,int MODE,int DM,bool DRY=false> __device__ __forceinline__ void attn_unit(int b,int h,int qb,const bf16*Q,const bf16*__restrict__ K,const bf16*__restrict__ V,bf16*O,const bf16*__restrict__ Z,const float*__restrict__ XP,const int*__restrict__ TS,volatile unsigned*lw,unsigned nxt,cha ...
;     ...
;         _Pragma("unroll") for(int c=0;c<8;++c){ const bf16x8 qv=*reinterpret_cast<const bf16x8*>(qp+c*8);
;           _Pragma("unroll") for(int j=0;j<8;++j){ const float qf=__uint_as_float(((unsigned)(unsigned short)qv[j])<<16);
;             _Pragma("unroll") for(int n=0;n<8;++n)g[n]+=qf*kbs[n*64+c*8+j]; } }
	v_lshlrev_b32_e32 v40, 16, v98
	v_fmac_f32_e32 v39, v116, v40
	v_fmac_f32_e32 v38, v120, v40
	v_fmac_f32_e32 v37, v124, v40
	v_fmac_f32_e32 v36, v128, v40
	v_fmac_f32_e32 v35, v132, v40
	v_fmac_f32_e32 v34, v136, v40
	v_fmac_f32_e32 v33, v140, v40
	v_fmac_f32_e32 v32, v76, v40
	v_and_b32_e32 v41, 0xffff0000, v98
	v_fmac_f32_e32 v39, v117, v41
	v_fmac_f32_e32 v38, v121, v41
	v_fmac_f32_e32 v37, v125, v41
	v_fmac_f32_e32 v36, v129, v41
	v_fmac_f32_e32 v35, v133, v41
	v_fmac_f32_e32 v34, v137, v41
	v_fmac_f32_e32 v33, v141, v41
	v_fmac_f32_e32 v32, v77, v41
	v_lshlrev_b32_e32 v40, 16, v99
	v_fmac_f32_e32 v39, v118, v40
	v_fmac_f32_e32 v38, v122, v40
	v_fmac_f32_e32 v37, v126, v40
	v_fmac_f32_e32 v36, v130, v40
	v_fmac_f32_e32 v35, v134, v40
	v_fmac_f32_e32 v34, v138, v40
	v_fmac_f32_e32 v33, v142, v40
	v_fmac_f32_e32 v32, v78, v40
	v_and_b32_e32 v41, 0xffff0000, v99
	v_fmac_f32_e32 v39, v119, v41
	v_fmac_f32_e32 v38, v123, v41
	v_fmac_f32_e32 v37, v127, v41
	v_fmac_f32_e32 v36, v131, v41
	v_fmac_f32_e32 v35, v135, v41
	v_fmac_f32_e32 v34, v139, v41
	v_fmac_f32_e32 v33, v143, v41
	v_fmac_f32_e32 v32, v79, v41
	ds_read_b128 v[116:119], v74 offset:144
	ds_read_b128 v[120:123], v74 offset:400
	ds_read_b128 v[124:127], v74 offset:656
	ds_read_b128 v[128:131], v74 offset:912
	ds_read_b128 v[132:135], v74 offset:1168
	ds_read_b128 v[136:139], v74 offset:1424
	ds_read_b128 v[140:143], v74 offset:1680
	ds_read_b128 v[76:79], v74 offset:1936
	s_waitcnt lgkmcnt(8)
	v_lshlrev_b32_e32 v40, 16, v100
	v_fmac_f32_e32 v39, v42, v40
	v_fmac_f32_e32 v38, v46, v40
	v_fmac_f32_e32 v37, v50, v40
	v_fmac_f32_e32 v36, v54, v40
	v_fmac_f32_e32 v35, v58, v40
	v_fmac_f32_e32 v34, v62, v40
	v_fmac_f32_e32 v33, v66, v40
	v_fmac_f32_e32 v32, v70, v40
	v_and_b32_e32 v41, 0xffff0000, v100
	v_fmac_f32_e32 v39, v43, v41
	v_fmac_f32_e32 v38, v47, v41
	v_fmac_f32_e32 v37, v51, v41
	v_fmac_f32_e32 v36, v55, v41
	v_fmac_f32_e32 v35, v59, v41
	v_fmac_f32_e32 v34, v63, v41
	v_fmac_f32_e32 v33, v67, v41
	v_fmac_f32_e32 v32, v71, v41
	v_lshlrev_b32_e32 v40, 16, v101
	v_fmac_f32_e32 v39, v44, v40
	v_fmac_f32_e32 v38, v48, v40
	v_fmac_f32_e32 v37, v52, v40
	v_fmac_f32_e32 v36, v56, v40
	v_fmac_f32_e32 v35, v60, v40
	v_fmac_f32_e32 v34, v64, v40
	v_fmac_f32_e32 v33, v68, v40
	v_fmac_f32_e32 v32, v72, v40
	v_and_b32_e32 v41, 0xffff0000, v101
	v_fmac_f32_e32 v39, v45, v41
	v_fmac_f32_e32 v38, v49, v41
	v_fmac_f32_e32 v37, v53, v41
	v_fmac_f32_e32 v36, v57, v41
	v_fmac_f32_e32 v35, v61, v41
	v_fmac_f32_e32 v34, v65, v41
	v_fmac_f32_e32 v33, v69, v41
	v_fmac_f32_e32 v32, v73, v41
	ds_read_b128 v[42:45], v74 offset:160
	ds_read_b128 v[46:49], v74 offset:416
	ds_read_b128 v[50:53], v74 offset:672
	ds_read_b128 v[54:57], v74 offset:928
	ds_read_b128 v[58:61], v74 offset:1184
	ds_read_b128 v[62:65], v74 offset:1440
	ds_read_b128 v[66:69], v74 offset:1696
	ds_read_b128 v[70:73], v74 offset:1952
	s_waitcnt lgkmcnt(8)
	v_lshlrev_b32_e32 v40, 16, v102
	v_fmac_f32_e32 v39, v116, v40
	v_fmac_f32_e32 v38, v120, v40
	v_fmac_f32_e32 v37, v124, v40
	v_fmac_f32_e32 v36, v128, v40
	v_fmac_f32_e32 v35, v132, v40
	v_fmac_f32_e32 v34, v136, v40
	v_fmac_f32_e32 v33, v140, v40
	v_fmac_f32_e32 v32, v76, v40
	v_and_b32_e32 v41, 0xffff0000, v102
	v_fmac_f32_e32 v39, v117, v41
	v_fmac_f32_e32 v38, v121, v41
	v_fmac_f32_e32 v37, v125, v41
	v_fmac_f32_e32 v36, v129, v41
	v_fmac_f32_e32 v35, v133, v41
	v_fmac_f32_e32 v34, v137, v41
	v_fmac_f32_e32 v33, v141, v41
	v_fmac_f32_e32 v32, v77, v41
	v_lshlrev_b32_e32 v40, 16, v103
	v_fmac_f32_e32 v39, v118, v40
	v_fmac_f32_e32 v38, v122, v40
	v_fmac_f32_e32 v37, v126, v40
	v_fmac_f32_e32 v36, v130, v40
	v_fmac_f32_e32 v35, v134, v40
	v_fmac_f32_e32 v34, v138, v40
	v_fmac_f32_e32 v33, v142, v40
	v_fmac_f32_e32 v32, v78, v40
	v_and_b32_e32 v41, 0xffff0000, v103
	v_fmac_f32_e32 v39, v119, v41
	v_fmac_f32_e32 v38, v123, v41
	v_fmac_f32_e32 v37, v127, v41
	v_fmac_f32_e32 v36, v131, v41
	v_fmac_f32_e32 v35, v135, v41
	v_fmac_f32_e32 v34, v139, v41
	v_fmac_f32_e32 v33, v143, v41
	v_fmac_f32_e32 v32, v79, v41
	ds_read_b128 v[116:119], v74 offset:176
	ds_read_b128 v[120:123], v74 offset:432
	ds_read_b128 v[124:127], v74 offset:688
	ds_read_b128 v[128:131], v74 offset:944
	ds_read_b128 v[132:135], v74 offset:1200
	ds_read_b128 v[136:139], v74 offset:1456
	ds_read_b128 v[140:143], v74 offset:1712
	ds_read_b128 v[76:79], v74 offset:1968
	s_waitcnt lgkmcnt(8)
	v_lshlrev_b32_e32 v40, 16, v104
	v_fmac_f32_e32 v39, v42, v40
	v_fmac_f32_e32 v38, v46, v40
	v_fmac_f32_e32 v37, v50, v40
	v_fmac_f32_e32 v36, v54, v40
	v_fmac_f32_e32 v35, v58, v40
	v_fmac_f32_e32 v34, v62, v40
	v_fmac_f32_e32 v33, v66, v40
	v_fmac_f32_e32 v32, v70, v40
	v_and_b32_e32 v41, 0xffff0000, v104
	v_fmac_f32_e32 v39, v43, v41
	v_fmac_f32_e32 v38, v47, v41
	v_fmac_f32_e32 v37, v51, v41
	v_fmac_f32_e32 v36, v55, v41
	v_fmac_f32_e32 v35, v59, v41
	v_fmac_f32_e32 v34, v63, v41
	v_fmac_f32_e32 v33, v67, v41
	v_fmac_f32_e32 v32, v71, v41
	v_lshlrev_b32_e32 v40, 16, v105
	v_fmac_f32_e32 v39, v44, v40
	v_fmac_f32_e32 v38, v48, v40
	v_fmac_f32_e32 v37, v52, v40
	v_fmac_f32_e32 v36, v56, v40
	v_fmac_f32_e32 v35, v60, v40
	v_fmac_f32_e32 v34, v64, v40
	v_fmac_f32_e32 v33, v68, v40
	v_fmac_f32_e32 v32, v72, v40
	v_and_b32_e32 v41, 0xffff0000, v105
	v_fmac_f32_e32 v39, v45, v41
	v_fmac_f32_e32 v38, v49, v41
	v_fmac_f32_e32 v37, v53, v41
	v_fmac_f32_e32 v36, v57, v41
	v_fmac_f32_e32 v35, v61, v41
	v_fmac_f32_e32 v34, v65, v41
	v_fmac_f32_e32 v33, v69, v41
	v_fmac_f32_e32 v32, v73, v41
	ds_read_b128 v[42:45], v74 offset:192
	ds_read_b128 v[46:49], v74 offset:448
	ds_read_b128 v[50:53], v74 offset:704
	ds_read_b128 v[54:57], v74 offset:960
	ds_read_b128 v[58:61], v74 offset:1216
	ds_read_b128 v[62:65], v74 offset:1472
	ds_read_b128 v[66:69], v74 offset:1728
	ds_read_b128 v[70:73], v74 offset:1984
	s_waitcnt lgkmcnt(8)
; template<int THRL,int MODE,int DM,bool DRY=false> __device__ __forceinline__ void attn_unit(int b,int h,int qb,const bf16*Q,const bf16*__restrict__ K,const bf16*__restrict__ V,bf16*O,const bf16*__restrict__ Z,const float*__restrict__ XP,const int*__restrict__ TS,volatile unsigned*lw,unsigned nxt,cha ...
;     ...
;         _Pragma("unroll") for(int c=0;c<8;++c){ const bf16x8 qv=*reinterpret_cast<const bf16x8*>(qp+c*8);
;           _Pragma("unroll") for(int j=0;j<8;++j){ const float qf=__uint_as_float(((unsigned)(unsigned short)qv[j])<<16);
;             _Pragma("unroll") for(int n=0;n<8;++n)g[n]+=qf*kbs[n*64+c*8+j]; } }
	v_lshlrev_b32_e32 v40, 16, v106
	v_fmac_f32_e32 v39, v116, v40
	v_fmac_f32_e32 v38, v120, v40
	v_fmac_f32_e32 v37, v124, v40
	v_fmac_f32_e32 v36, v128, v40
	v_fmac_f32_e32 v35, v132, v40
	v_fmac_f32_e32 v34, v136, v40
	v_fmac_f32_e32 v33, v140, v40
	v_fmac_f32_e32 v32, v76, v40
	v_and_b32_e32 v41, 0xffff0000, v106
	v_fmac_f32_e32 v39, v117, v41
	v_fmac_f32_e32 v38, v121, v41
	v_fmac_f32_e32 v37, v125, v41
	v_fmac_f32_e32 v36, v129, v41
	v_fmac_f32_e32 v35, v133, v41
	v_fmac_f32_e32 v34, v137, v41
	v_fmac_f32_e32 v33, v141, v41
	v_fmac_f32_e32 v32, v77, v41
	v_lshlrev_b32_e32 v40, 16, v107
	v_fmac_f32_e32 v39, v118, v40
	v_fmac_f32_e32 v38, v122, v40
	v_fmac_f32_e32 v37, v126, v40
	v_fmac_f32_e32 v36, v130, v40
	v_fmac_f32_e32 v35, v134, v40
	v_fmac_f32_e32 v34, v138, v40
	v_fmac_f32_e32 v33, v142, v40
	v_fmac_f32_e32 v32, v78, v40
	v_and_b32_e32 v41, 0xffff0000, v107
	v_fmac_f32_e32 v39, v119, v41
	v_fmac_f32_e32 v38, v123, v41
	v_fmac_f32_e32 v37, v127, v41
	v_fmac_f32_e32 v36, v131, v41
	v_fmac_f32_e32 v35, v135, v41
	v_fmac_f32_e32 v34, v139, v41
	v_fmac_f32_e32 v33, v143, v41
	v_fmac_f32_e32 v32, v79, v41
	ds_read_b128 v[116:119], v74 offset:208
	ds_read_b128 v[120:123], v74 offset:464
	ds_read_b128 v[124:127], v74 offset:720
	ds_read_b128 v[128:131], v74 offset:976
	ds_read_b128 v[132:135], v74 offset:1232
	ds_read_b128 v[136:139], v74 offset:1488
	ds_read_b128 v[140:143], v74 offset:1744
	ds_read_b128 v[76:79], v74 offset:2000
	s_waitcnt lgkmcnt(8)
	v_lshlrev_b32_e32 v40, 16, v108
	v_fmac_f32_e32 v39, v42, v40
	v_fmac_f32_e32 v38, v46, v40
	v_fmac_f32_e32 v37, v50, v40
	v_fmac_f32_e32 v36, v54, v40
	v_fmac_f32_e32 v35, v58, v40
	v_fmac_f32_e32 v34, v62, v40
	v_fmac_f32_e32 v33, v66, v40
	v_fmac_f32_e32 v32, v70, v40
	v_and_b32_e32 v41, 0xffff0000, v108
	v_fmac_f32_e32 v39, v43, v41
	v_fmac_f32_e32 v38, v47, v41
	v_fmac_f32_e32 v37, v51, v41
	v_fmac_f32_e32 v36, v55, v41
	v_fmac_f32_e32 v35, v59, v41
	v_fmac_f32_e32 v34, v63, v41
	v_fmac_f32_e32 v33, v67, v41
	v_fmac_f32_e32 v32, v71, v41
	v_lshlrev_b32_e32 v40, 16, v109
	v_fmac_f32_e32 v39, v44, v40
	v_fmac_f32_e32 v38, v48, v40
	v_fmac_f32_e32 v37, v52, v40
	v_fmac_f32_e32 v36, v56, v40
	v_fmac_f32_e32 v35, v60, v40
	v_fmac_f32_e32 v34, v64, v40
	v_fmac_f32_e32 v33, v68, v40
	v_fmac_f32_e32 v32, v72, v40
	v_and_b32_e32 v41, 0xffff0000, v109
	v_fmac_f32_e32 v39, v45, v41
	v_fmac_f32_e32 v38, v49, v41
	v_fmac_f32_e32 v37, v53, v41
	v_fmac_f32_e32 v36, v57, v41
	v_fmac_f32_e32 v35, v61, v41
	v_fmac_f32_e32 v34, v65, v41
	v_fmac_f32_e32 v33, v69, v41
	v_fmac_f32_e32 v32, v73, v41
	ds_read_b128 v[42:45], v74 offset:224
	ds_read_b128 v[46:49], v74 offset:480
	ds_read_b128 v[50:53], v74 offset:736
	ds_read_b128 v[54:57], v74 offset:992
	ds_read_b128 v[58:61], v74 offset:1248
	ds_read_b128 v[62:65], v74 offset:1504
	ds_read_b128 v[66:69], v74 offset:1760
	ds_read_b128 v[70:73], v74 offset:2016
	s_waitcnt lgkmcnt(8)
	v_lshlrev_b32_e32 v40, 16, v110
	v_fmac_f32_e32 v39, v116, v40
	v_fmac_f32_e32 v38, v120, v40
	v_fmac_f32_e32 v37, v124, v40
	v_fmac_f32_e32 v36, v128, v40
	v_fmac_f32_e32 v35, v132, v40
	v_fmac_f32_e32 v34, v136, v40
	v_fmac_f32_e32 v33, v140, v40
	v_fmac_f32_e32 v32, v76, v40
	v_and_b32_e32 v41, 0xffff0000, v110
	v_fmac_f32_e32 v39, v117, v41
	v_fmac_f32_e32 v38, v121, v41
	v_fmac_f32_e32 v37, v125, v41
	v_fmac_f32_e32 v36, v129, v41
	v_fmac_f32_e32 v35, v133, v41
	v_fmac_f32_e32 v34, v137, v41
	v_fmac_f32_e32 v33, v141, v41
	v_fmac_f32_e32 v32, v77, v41
	v_lshlrev_b32_e32 v40, 16, v111
	v_fmac_f32_e32 v39, v118, v40
	v_fmac_f32_e32 v38, v122, v40
	v_fmac_f32_e32 v37, v126, v40
	v_fmac_f32_e32 v36, v130, v40
	v_fmac_f32_e32 v35, v134, v40
	v_fmac_f32_e32 v34, v138, v40
	v_fmac_f32_e32 v33, v142, v40
	v_fmac_f32_e32 v32, v78, v40
	v_and_b32_e32 v41, 0xffff0000, v111
	v_fmac_f32_e32 v39, v119, v41
	v_fmac_f32_e32 v38, v123, v41
	v_fmac_f32_e32 v37, v127, v41
	v_fmac_f32_e32 v36, v131, v41
	v_fmac_f32_e32 v35, v135, v41
	v_fmac_f32_e32 v34, v139, v41
	v_fmac_f32_e32 v33, v143, v41
	v_fmac_f32_e32 v32, v79, v41
	ds_read_b128 v[116:119], v74 offset:240
	ds_read_b128 v[120:123], v74 offset:496
	ds_read_b128 v[124:127], v74 offset:752
	ds_read_b128 v[128:131], v74 offset:1008
	ds_read_b128 v[132:135], v74 offset:1264
	ds_read_b128 v[136:139], v74 offset:1520
	ds_read_b128 v[140:143], v74 offset:1776
	ds_read_b128 v[76:79], v74 offset:2032
	s_waitcnt lgkmcnt(8)
	v_lshlrev_b32_e32 v40, 16, v112
	v_fmac_f32_e32 v39, v42, v40
	v_fmac_f32_e32 v38, v46, v40
	v_fmac_f32_e32 v37, v50, v40
	v_fmac_f32_e32 v36, v54, v40
	v_fmac_f32_e32 v35, v58, v40
	v_fmac_f32_e32 v34, v62, v40
	v_fmac_f32_e32 v33, v66, v40
	v_fmac_f32_e32 v32, v70, v40
	v_and_b32_e32 v41, 0xffff0000, v112
	v_fmac_f32_e32 v39, v43, v41
	v_fmac_f32_e32 v38, v47, v41
	v_fmac_f32_e32 v37, v51, v41
	v_fmac_f32_e32 v36, v55, v41
	v_fmac_f32_e32 v35, v59, v41
	v_fmac_f32_e32 v34, v63, v41
	v_fmac_f32_e32 v33, v67, v41
	v_fmac_f32_e32 v32, v71, v41
	v_lshlrev_b32_e32 v40, 16, v113
	v_fmac_f32_e32 v39, v44, v40
	v_fmac_f32_e32 v38, v48, v40
	v_fmac_f32_e32 v37, v52, v40
	v_fmac_f32_e32 v36, v56, v40
	v_fmac_f32_e32 v35, v60, v40
	v_fmac_f32_e32 v34, v64, v40
	v_fmac_f32_e32 v33, v68, v40
	v_fmac_f32_e32 v32, v72, v40
	v_and_b32_e32 v41, 0xffff0000, v113
	v_fmac_f32_e32 v39, v45, v41
	v_fmac_f32_e32 v38, v49, v41
	v_fmac_f32_e32 v37, v53, v41
	v_fmac_f32_e32 v36, v57, v41
	v_fmac_f32_e32 v35, v61, v41
	v_fmac_f32_e32 v34, v65, v41
	v_fmac_f32_e32 v33, v69, v41
	v_fmac_f32_e32 v32, v73, v41
	s_waitcnt lgkmcnt(0)
; template<int THRL,int MODE,int DM,bool DRY=false> __device__ __forceinline__ void attn_unit(int b,int h,int qb,const bf16*Q,const bf16*__restrict__ K,const bf16*__restrict__ V,bf16*O,const bf16*__restrict__ Z,const float*__restrict__ XP,const int*__restrict__ TS,volatile unsigned*lw,unsigned nxt,cha ...
;     ...
;         _Pragma("unroll") for(int c=0;c<8;++c){ const bf16x8 qv=*reinterpret_cast<const bf16x8*>(qp+c*8);
;           _Pragma("unroll") for(int j=0;j<8;++j){ const float qf=__uint_as_float(((unsigned)(unsigned short)qv[j])<<16);
;             _Pragma("unroll") for(int n=0;n<8;++n)g[n]+=qf*kbs[n*64+c*8+j]; } }
;         m=0u;
;         _Pragma("unroll") for(int it=0;it<3;++it){ float best=-INFINITY; int bi=0;
;           _Pragma("unroll") for(int n=0;n<8;++n){ const bool ok=(n<qb)&&!((m>>n)&1u)&&(g[n]>best); best=ok?g[n]:best; bi=ok?n:bi; }
;           m|=1u<<bi; } }
;       sm[tid]=m; }
	v_lshlrev_b32_e32 v40, 16, v114
	v_fmac_f32_e32 v39, v116, v40
	v_fmac_f32_e32 v38, v120, v40
	v_fmac_f32_e32 v37, v124, v40
	v_fmac_f32_e32 v36, v128, v40
	v_fmac_f32_e32 v35, v132, v40
	v_fmac_f32_e32 v34, v136, v40
	v_fmac_f32_e32 v33, v140, v40
	v_fmac_f32_e32 v32, v76, v40
	v_and_b32_e32 v41, 0xffff0000, v114
	v_fmac_f32_e32 v39, v117, v41
	v_fmac_f32_e32 v38, v121, v41
	v_fmac_f32_e32 v37, v125, v41
	v_fmac_f32_e32 v36, v129, v41
	v_fmac_f32_e32 v35, v133, v41
	v_fmac_f32_e32 v34, v137, v41
	v_fmac_f32_e32 v33, v141, v41
	v_fmac_f32_e32 v32, v77, v41
	v_lshlrev_b32_e32 v40, 16, v115
	v_fmac_f32_e32 v39, v118, v40
	v_fmac_f32_e32 v38, v122, v40
	v_fmac_f32_e32 v37, v126, v40
	v_fmac_f32_e32 v36, v130, v40
	v_fmac_f32_e32 v35, v134, v40
	v_fmac_f32_e32 v34, v138, v40
	v_fmac_f32_e32 v33, v142, v40
	v_fmac_f32_e32 v32, v78, v40
	v_and_b32_e32 v41, 0xffff0000, v115
	v_fmac_f32_e32 v39, v119, v41
	v_fmac_f32_e32 v38, v123, v41
	v_fmac_f32_e32 v37, v127, v41
	v_fmac_f32_e32 v36, v131, v41
	v_fmac_f32_e32 v35, v135, v41
	v_fmac_f32_e32 v34, v139, v41
	v_fmac_f32_e32 v33, v143, v41
	v_fmac_f32_e32 v32, v79, v41
	v_cmp_lg_f32_e32 vcc, s10, v39
	s_nop 1
	v_cndmask_b32_e32 v40, v234, v39, vcc
	v_cmp_gt_f32_e32 vcc, v38, v40
	s_nop 1
	v_cndmask_b32_e32 v40, v40, v38, vcc
	v_cndmask_b32_e64 v41, 0, 1, vcc
	v_cmp_gt_f32_e32 vcc, v37, v40
	s_nop 1
	v_cndmask_b32_e32 v40, v40, v37, vcc
	v_cndmask_b32_e64 v41, v41, 2, vcc
	v_cmp_gt_f32_e32 vcc, v36, v40
	s_nop 1
	v_cndmask_b32_e32 v40, v40, v36, vcc
	v_cndmask_b32_e64 v41, v41, 3, vcc
	v_cmp_gt_f32_e32 vcc, v35, v40
	s_and_b64 vcc, s[74:75], vcc
	s_cmp_gt_u32 s95, 5
	v_cndmask_b32_e32 v40, v40, v35, vcc
	v_cndmask_b32_e64 v41, v41, 4, vcc
	s_cselect_b64 s[76:77], -1, 0
	v_cmp_gt_f32_e32 vcc, v34, v40
	s_and_b64 vcc, s[76:77], vcc
	s_cmp_lt_u32 s92, -7
	v_cndmask_b32_e32 v40, v40, v34, vcc
	v_cndmask_b32_e64 v41, v41, 5, vcc
	s_cselect_b64 s[78:79], -1, 0
	v_cmp_gt_f32_e32 vcc, v33, v40
	s_and_b64 vcc, s[78:79], vcc
	s_cmp_gt_u32 s95, 7
	v_cndmask_b32_e32 v40, v40, v33, vcc
	v_cndmask_b32_e64 v41, v41, 6, vcc
	s_cselect_b64 s[80:81], -1, 0
	v_cmp_gt_f32_e32 vcc, v32, v40
	s_and_b64 s[8:9], s[80:81], vcc
	v_cndmask_b32_e64 v40, v41, 7, s[8:9]
	v_cmp_eq_u32_e64 s[8:9], 0, v40
	v_cmp_nlg_f32_e32 vcc, s10, v39
	v_lshlrev_b32_e64 v41, v40, 1
	s_or_b64 s[8:9], s[8:9], vcc
	v_cndmask_b32_e64 v40, v39, v234, s[8:9]
	v_and_b32_e32 v42, 2, v41
	v_cmp_eq_u32_e64 s[8:9], 0, v42
	v_cmp_gt_f32_e64 s[10:11], v38, v40
	s_and_b64 s[8:9], s[8:9], s[10:11]
	v_cndmask_b32_e64 v40, v40, v38, s[8:9]
	v_and_b32_e32 v43, 4, v41
	v_cndmask_b32_e64 v42, 0, 1, s[8:9]
	v_cmp_eq_u32_e64 s[8:9], 0, v43
	v_cmp_gt_f32_e64 s[10:11], v37, v40
	s_and_b64 s[18:19], s[8:9], s[10:11]
	v_cndmask_b32_e64 v40, v40, v37, s[18:19]
	v_and_b32_e32 v43, 8, v41
	v_cmp_eq_u32_e64 s[8:9], 0, v43
	v_cmp_gt_f32_e64 s[10:11], v36, v40
	s_and_b64 s[16:17], s[8:9], s[10:11]
	v_and_b32_e32 v43, 16, v41
	v_cndmask_b32_e64 v40, v40, v36, s[16:17]
	v_cmp_eq_u32_e64 s[8:9], 0, v43
	s_and_b64 s[10:11], s[74:75], s[8:9]
	v_cmp_gt_f32_e64 s[8:9], v35, v40
	s_and_b64 s[14:15], s[10:11], s[8:9]
	v_and_b32_e32 v43, 32, v41
	v_cndmask_b32_e64 v40, v40, v35, s[14:15]
	v_cmp_eq_u32_e64 s[8:9], 0, v43
	s_and_b64 s[10:11], s[76:77], s[8:9]
	v_cmp_gt_f32_e64 s[8:9], v34, v40
	s_and_b64 s[12:13], s[10:11], s[8:9]
	v_and_b32_e32 v43, 64, v41
	v_cndmask_b32_e64 v40, v40, v34, s[12:13]
	v_cmp_eq_u32_e64 s[8:9], 0, v43
	s_and_b64 s[10:11], s[78:79], s[8:9]
	v_cmp_gt_f32_e64 s[8:9], v33, v40
	s_and_b64 s[10:11], s[10:11], s[8:9]
	v_and_b32_e32 v43, 0x80, v41
	v_cndmask_b32_e64 v40, v40, v33, s[10:11]
	v_cmp_eq_u32_e64 s[8:9], 0, v43
	s_and_b64 s[42:43], s[80:81], s[8:9]
	v_cmp_gt_f32_e64 s[8:9], v32, v40
	v_lshlrev_b32_e64 v40, v42, 1
	v_cndmask_b32_e64 v40, v40, 4, s[18:19]
	v_cndmask_b32_e64 v40, v40, 8, s[16:17]
	v_cndmask_b32_e64 v40, v40, 16, s[14:15]
	v_cndmask_b32_e64 v40, v40, 32, s[12:13]
	s_and_b64 s[8:9], s[42:43], s[8:9]
	v_cndmask_b32_e64 v40, v40, 64, s[10:11]
	v_cndmask_b32_e64 v40, v40, v235, s[8:9]
	v_or_b32_e32 v42, v40, v41
	v_and_b32_e32 v43, 1, v42
	v_cmp_eq_u32_e64 s[8:9], 1, v43
	s_or_b64 vcc, s[8:9], vcc
	v_cndmask_b32_e32 v39, v39, v234, vcc
	v_bitop3_b32 v43, v40, 2, v41 bitop3:0xc8
	v_cmp_eq_u32_e32 vcc, 0, v43
	v_cmp_gt_f32_e64 s[8:9], v38, v39
	s_and_b64 vcc, vcc, s[8:9]
	v_cndmask_b32_e32 v38, v39, v38, vcc
	v_bitop3_b32 v39, v40, 4, v41 bitop3:0xc8
	v_cndmask_b32_e64 v43, 0, 1, vcc
	v_cmp_eq_u32_e32 vcc, 0, v39
	v_cmp_gt_f32_e64 s[8:9], v37, v38
	s_and_b64 s[8:9], vcc, s[8:9]
	s_nop 0
	v_cndmask_b32_e64 v37, v38, v37, s[8:9]
	v_bitop3_b32 v38, v40, 8, v41 bitop3:0xc8
	v_cmp_eq_u32_e32 vcc, 0, v38
	v_cmp_gt_f32_e64 s[10:11], v36, v37
	s_and_b64 vcc, vcc, s[10:11]
	v_cndmask_b32_e32 v36, v37, v36, vcc
	v_bitop3_b32 v37, v40, 16, v41 bitop3:0xc8
	v_cmp_eq_u32_e64 s[10:11], 0, v37
	s_and_b64 s[12:13], s[74:75], s[10:11]
	v_cmp_gt_f32_e64 s[10:11], v35, v36
	s_and_b64 s[10:11], s[12:13], s[10:11]
	s_nop 0
	v_cndmask_b32_e64 v35, v36, v35, s[10:11]
	v_bitop3_b32 v36, v40, 32, v41 bitop3:0xc8
	v_cmp_eq_u32_e64 s[12:13], 0, v36
	s_and_b64 s[14:15], s[76:77], s[12:13]
	v_cmp_gt_f32_e64 s[12:13], v34, v35
	s_and_b64 s[12:13], s[14:15], s[12:13]
	s_nop 0
	v_cndmask_b32_e64 v34, v35, v34, s[12:13]
	v_bitop3_b32 v35, v40, 64, v41 bitop3:0xc8
	v_cmp_eq_u32_e64 s[14:15], 0, v35
	s_and_b64 s[16:17], s[78:79], s[14:15]
	v_cmp_gt_f32_e64 s[14:15], v33, v34
	s_and_b64 s[14:15], s[16:17], s[14:15]
	s_movk_i32 s16, 0x80
	v_cndmask_b32_e64 v33, v34, v33, s[14:15]
	v_bitop3_b32 v34, v40, s16, v41 bitop3:0xc8
	v_cmp_eq_u32_e64 s[16:17], 0, v34
	s_and_b64 s[18:19], s[80:81], s[16:17]
	v_cmp_gt_f32_e64 s[16:17], v32, v33
	v_lshlrev_b32_e64 v32, v43, 1
	v_cndmask_b32_e64 v32, v32, 4, s[8:9]
	v_cndmask_b32_e64 v32, v32, 8, vcc
	v_cndmask_b32_e64 v32, v32, 16, s[10:11]
	v_cndmask_b32_e64 v32, v32, 32, s[12:13]
	s_and_b64 s[16:17], s[18:19], s[16:17]
	v_cndmask_b32_e64 v32, v32, 64, s[14:15]
	v_cndmask_b32_e64 v32, v32, v235, s[16:17]
	v_readlane_b32 s78, v253, 1
	v_or_b32_e32 v32, v32, v42
	v_readlane_b32 s79, v253, 2

; #define WAIT_BAR(N) asm volatile("s_waitcnt vmcnt(" #N ") lgkmcnt(0)\n\ts_barrier":::"memory")
;   #define CMASK(P0,P1,t) do{int jb_=(t)-(NT-4); if(jb_>=0)cmask(P0,P1,jb_,qrel,hi);}while(0)
;   #define CMASK(P0,P1,t) do{}while(0)
;   #define CMASK(P0,P1,t) do{int jb_=(t)-(NT-4); if(jb_>=0)cmask(P0,P1,jb_,qrel,hi);}while(0)
; template<int THRL,int MODE,int DM,bool DRY=false> __device__ __forceinline__ void attn_unit(int b,int h,int qb,const bf16*Q,const bf16*__restrict__ K,const bf16*__restrict__ V,bf16*O,const bf16*__restrict__ Z,const float*__restrict__ XP,const int*__restrict__ TS,volatile unsigned*lw,unsigned nxt,cha ...
;     ...
;     asm volatile("s_waitcnt vmcnt(0) lgkmcnt(0)\n\ts_barrier":::"memory");
;     sel=sm[qrel];
;   }
;   WAIT_BAR(3); float frow=0.f; if constexpr(MODE==1)frow=((const float*)(shm+XOFF))[q0+qrel];
;   qkt(pA0,pA1,Kbase,qr,NEGM,r32,hi);asm volatile("s_nop 15\n\ts_nop 7":"+v"(pA0),"+v"(pA1));XMASK(pA0,pA1,0);CMASK(pA0,pA1,0);
.LBB0_898:
	s_or_b64 exec, exec, s[72:73]
	v_lshlrev_b32_e32 v32, 10, v238
	v_lshlrev_b32_e32 v33, 4, v237
	v_or_b32_e32 v246, s96, v237
	v_add3_u32 v248, 0, v32, v33
	v_lshl_add_u32 v32, v246, 2, 0
	s_cmp_lt_u32 s95, 4
	s_cbranch_scc1 .Lmoba_small_sel
	s_waitcnt vmcnt(0) lgkmcnt(0)
	s_barrier
	v_add_u32_e32 v32, 0x15800, v32
	ds_read_b32 v249, v32
	s_branch .Lmoba_sel_done
.Lmoba_small_sel:
	s_lshl_b32 s98, -1, s95
	s_not_b32 s98, s98
	v_mov_b32_e32 v249, s98
.Lmoba_sel_done:
	s_waitcnt vmcnt(3) lgkmcnt(0)
	s_barrier
	ds_read_b128 v[32:35], v248
	s_cmp_lg_u32 s95, 0
	s_cselect_b64 s[8:9], -1, 0
	s_cmp_eq_u32 s95, 0
	s_waitcnt lgkmcnt(0)
	v_mfma_f32_32x32x16_bf16 v[64:79], v[32:35], v[156:159], v[16:31]
	ds_read_b128 v[32:35], v248 offset:512
	s_waitcnt lgkmcnt(0)
	v_mfma_f32_32x32x16_bf16 v[16:31], v[32:35], v[156:159], v[16:31]
	ds_read_b128 v[32:35], v248 offset:2048
	s_waitcnt lgkmcnt(0)
	v_mfma_f32_32x32x16_bf16 v[64:79], v[32:35], v[152:155], v[64:79]
	ds_read_b128 v[32:35], v248 offset:2560
	s_waitcnt lgkmcnt(0)
	v_mfma_f32_32x32x16_bf16 v[16:31], v[32:35], v[152:155], v[16:31]
	ds_read_b128 v[32:35], v248 offset:4096
	s_waitcnt lgkmcnt(0)
	v_mfma_f32_32x32x16_bf16 v[64:79], v[32:35], v[148:151], v[64:79]
	ds_read_b128 v[32:35], v248 offset:4608
	s_waitcnt lgkmcnt(0)
	v_mfma_f32_32x32x16_bf16 v[16:31], v[32:35], v[148:151], v[16:31]
	ds_read_b128 v[32:35], v248 offset:6144
	s_waitcnt lgkmcnt(0)
	v_mfma_f32_32x32x16_bf16 v[64:79], v[32:35], v[144:147], v[64:79]
	ds_read_b128 v[32:35], v248 offset:6656
	s_waitcnt lgkmcnt(0)
	v_mfma_f32_32x32x16_bf16 v[16:31], v[32:35], v[144:147], v[16:31]
	s_nop 15
	s_nop 7
	s_cbranch_scc1 .LBB0_971
	v_and_b32_e32 v32, 1, v249
	v_cmp_eq_u32_e32 vcc, 0, v32
	s_nop 5
	v_cndmask_b32_e32 v48, v64, v236, vcc
	s_nop 1
	v_cndmask_b32_e32 v32, v16, v236, vcc
	v_cndmask_b32_e32 v49, v65, v236, vcc
	v_cndmask_b32_e32 v33, v17, v236, vcc
	v_cndmask_b32_e32 v50, v66, v236, vcc
	v_cndmask_b32_e32 v34, v18, v236, vcc
	v_cndmask_b32_e32 v51, v67, v236, vcc
	v_cndmask_b32_e32 v35, v19, v236, vcc
	v_cndmask_b32_e32 v52, v68, v236, vcc
	v_cndmask_b32_e32 v36, v20, v236, vcc
	v_cndmask_b32_e32 v53, v69, v236, vcc
	v_cndmask_b32_e32 v37, v21, v236, vcc
	v_cndmask_b32_e32 v54, v70, v236, vcc
	v_cndmask_b32_e32 v38, v22, v236, vcc
	v_cndmask_b32_e32 v55, v71, v236, vcc
	v_cndmask_b32_e32 v39, v23, v236, vcc
	v_cndmask_b32_e32 v56, v72, v236, vcc
	v_cndmask_b32_e32 v40, v24, v236, vcc
	v_cndmask_b32_e32 v57, v73, v236, vcc
	v_cndmask_b32_e32 v41, v25, v236, vcc
	v_cndmask_b32_e32 v58, v74, v236, vcc
	v_cndmask_b32_e32 v42, v26, v236, vcc
	v_cndmask_b32_e32 v59, v75, v236, vcc
	v_cndmask_b32_e32 v43, v27, v236, vcc
	v_cndmask_b32_e32 v60, v76, v236, vcc
	v_cndmask_b32_e32 v44, v28, v236, vcc
	v_cndmask_b32_e32 v61, v77, v236, vcc
	v_cndmask_b32_e32 v45, v29, v236, vcc
	v_cndmask_b32_e32 v62, v78, v236, vcc
	v_cndmask_b32_e32 v46, v30, v236, vcc
	v_cndmask_b32_e32 v63, v79, v236, vcc
	v_cndmask_b32_e32 v47, v31, v236, vcc
	v_lshlrev_b32_e32 v243, 2, v238
	s_cbranch_execnz .LBB0_901
